# attention tile loop: packed fp32 adds between MFMAs split into scalar adds (asm guide 7.5), dead adds removed, VOP3 adds re-encoded VOP2
# speedup vs baseline: 1.0079x; 1.0079x over previous
.LBB0_423:
	v_add_u32_e32 v81, s5, v206
	ds_read_b128 v[82:85], v81
	ds_read_b128 v[86:89], v81 offset:4096
	v_add_u32_e32 v90, s5, v207
	v_add_u32_e32 v94, s5, v208
	v_exp_f32_e32 v128, v128
	v_exp_f32_e32 v129, v129
	v_exp_f32_e32 v152, v96
	v_exp_f32_e32 v153, v97
	v_add_u32_e32 v81, s5, v209
	s_waitcnt lgkmcnt(1)
	v_mfma_f32_32x32x16_bf16 v[112:127], v[82:85], v[160:163], v[64:79]
	ds_read_b128 v[82:85], v90
	ds_read_b128 v[90:93], v90 offset:4096
	ds_read_b128 v[144:147], v94
	ds_read_b128 v[148:151], v94 offset:4096
	v_add_f32_e32 v154, v153, v152
	v_exp_f32_e32 v108, v108
	v_exp_f32_e32 v109, v109
	v_exp_f32_e32 v110, v110
	v_exp_f32_e32 v111, v111
	s_add_i32 s4, s4, 2
	s_waitcnt lgkmcnt(4)
	v_mfma_f32_32x32x16_bf16 v[216:231], v[86:89], v[160:163], v[64:79]
	ds_read_b128 v[86:89], v81
	ds_read_b128 v[94:97], v81 offset:4096
	v_add_f32_e32 v81, v129, v128
	v_add_f32_e32 v81, v154, v81
	v_cvt_pk_bf16_f32 v128, v128, v129
	s_add_i32 s5, s76, s77
	s_cmpk_eq_i32 s5, 0x2000
	s_waitcnt lgkmcnt(5)
	v_mfma_f32_32x32x16_bf16 v[112:127], v[82:85], v[164:167], v[112:127]
	v_exp_f32_e32 v83, v130
	v_exp_f32_e32 v84, v131
	v_exp_f32_e32 v85, v98
	v_exp_f32_e32 v98, v99
	v_exp_f32_e32 v99, v103
	v_cvt_pk_bf16_f32 v129, v83, v84
	v_exp_f32_e32 v103, v137
	s_waitcnt lgkmcnt(4)
	v_mfma_f32_32x32x16_bf16 v[216:231], v[90:93], v[164:167], v[216:231]
	v_add_f32_e32 v90, v84, v83
	v_add_f32_e32 v91, v98, v85
	v_add_f32_e32 v90, v91, v90
	v_add_f32_e32 v81, v90, v81
	v_exp_f32_e32 v90, v132
	v_exp_f32_e32 v91, v133
	v_exp_f32_e32 v92, v100
	v_exp_f32_e32 v93, v101
	s_waitcnt lgkmcnt(3)
	v_mfma_f32_32x32x16_bf16 v[112:127], v[144:147], v[168:171], v[112:127]
	v_cvt_pk_bf16_f32 v83, v85, v98
	v_add_f32_e32 v84, v91, v90
	v_add_f32_e32 v85, v93, v92
	v_add_f32_e32 v84, v85, v84
	v_cvt_pk_bf16_f32 v130, v90, v91
	v_exp_f32_e32 v85, v134
	v_exp_f32_e32 v90, v135
	s_waitcnt lgkmcnt(2)
	v_mfma_f32_32x32x16_bf16 v[216:231], v[148:151], v[168:171], v[216:231]
	v_exp_f32_e32 v98, v102
	v_add_f32_e32 v81, v84, v81
	v_add_f32_e32 v91, v90, v85
	v_exp_f32_e32 v102, v136
	v_exp_f32_e32 v136, v104
	v_exp_f32_e32 v137, v105
	v_cvt_pk_bf16_f32 v84, v92, v93
	s_waitcnt lgkmcnt(1)
	v_mfma_f32_32x32x16_bf16 v[112:127], v[86:89], v[172:175], v[112:127]
	v_add_f32_e32 v86, v99, v98
	v_add_f32_e32 v86, v86, v91
	v_add_f32_e32 v81, v86, v81
	ds_read_b64_tr_b16 v[86:87], v213 offset:40960
	ds_read_b64_tr_b16 v[88:89], v213 offset:43008
	v_cvt_pk_bf16_f32 v131, v85, v90
	v_add_f32_e32 v104, v103, v102
	v_add_f32_e32 v105, v137, v136
	s_waitcnt lgkmcnt(2)
	v_mfma_f32_32x32x16_bf16 v[216:231], v[94:97], v[172:175], v[216:231]
	ds_read_b64_tr_b16 v[90:91], v214 offset:40960
	ds_read_b64_tr_b16 v[92:93], v214 offset:43008
	ds_read_b64_tr_b16 v[94:95], v213 offset:45056
	ds_read_b64_tr_b16 v[96:97], v213 offset:47104
	v_cvt_pk_bf16_f32 v85, v98, v99
	v_cvt_pk_bf16_f32 v82, v152, v153
	s_cselect_b32 s8, s71, 0x2000
	s_cmpk_lg_i32 s5, 0x6000
	s_cselect_b32 s77, s8, 0
	s_add_u32 s38, s38, 0x40000
	s_waitcnt lgkmcnt(2)
	v_mfma_f32_32x32x16_bf16 v[32:47], v[90:93], v[128:131], v[32:47]
	v_add_f32_e32 v90, v105, v104
	v_add_f32_e32 v81, v90, v81
	v_cvt_pk_bf16_f32 v90, v102, v103
	v_exp_f32_e32 v91, v138
	v_exp_f32_e32 v92, v139
	v_exp_f32_e32 v138, v106
	v_exp_f32_e32 v106, v140
	v_mfma_f32_32x32x16_bf16 v[48:63], v[86:89], v[128:131], v[48:63]
	ds_read_b64_tr_b16 v[86:87], v215 offset:40960
	ds_read_b64_tr_b16 v[88:89], v215 offset:43008
	ds_read_b64_tr_b16 v[98:99], v214 offset:45056
	ds_read_b64_tr_b16 v[100:101], v214 offset:47104
	ds_read_b64_tr_b16 v[102:103], v248 offset:40960
	ds_read_b64_tr_b16 v[104:105], v248 offset:43008
	ds_read_b64_tr_b16 v[132:133], v215 offset:45056
	ds_read_b64_tr_b16 v[134:135], v215 offset:47104
	v_exp_f32_e32 v139, v107
	v_mov_b64_e32 v[158:159], v[230:231]
	s_addc_u32 s39, s39, 0
	s_add_i32 s75, s75, 0x20000
	s_and_b64 vcc, exec, s[6:7]
	s_waitcnt lgkmcnt(2)
	v_mfma_f32_32x32x16_bf16 v[0:15], v[102:105], v[128:131], v[0:15]
	v_exp_f32_e32 v102, v141
	v_exp_f32_e32 v103, v142
	v_exp_f32_e32 v104, v143
	v_add_f32_e32 v105, v92, v91
	v_cvt_pk_bf16_f32 v91, v91, v92
	v_cvt_pk_bf16_f32 v92, v106, v102
	v_cvt_pk_bf16_f32 v93, v103, v104
	v_mfma_f32_32x32x16_bf16 v[16:31], v[86:89], v[128:131], v[16:31]
	ds_read_b64_tr_b16 v[86:87], v248 offset:45056
	ds_read_b64_tr_b16 v[88:89], v248 offset:47104
	v_mov_b64_e32 v[156:157], v[228:229]
	v_mov_b64_e32 v[154:155], v[226:227]
	v_mov_b64_e32 v[152:153], v[224:225]
	v_mov_b64_e32 v[150:151], v[222:223]
	v_mov_b64_e32 v[148:149], v[220:221]
	v_mov_b64_e32 v[146:147], v[218:219]
	v_mfma_f32_32x32x16_bf16 v[48:63], v[94:97], v[90:93], v[48:63]
	v_add_f32_e32 v94, v139, v138
	v_add_f32_e32 v94, v94, v105
	v_add_f32_e32 v81, v94, v81
	v_add_f32_e32 v94, v102, v106
	v_add_f32_e32 v95, v109, v108
	v_add_f32_e32 v94, v95, v94
	v_add_f32_e32 v81, v94, v81
	v_mfma_f32_32x32x16_bf16 v[32:47], v[98:101], v[90:93], v[32:47]
	v_add_f32_e32 v94, v104, v103
	v_add_f32_e32 v95, v111, v110
	v_add_f32_e32 v94, v95, v94
	v_add_f32_e32 v106, v94, v81
	v_max_f32_e32 v81, v113, v113
	v_max_f32_e32 v94, v112, v112
	v_max_f32_e32 v81, v94, v81
	s_waitcnt lgkmcnt(2)
	v_mfma_f32_32x32x16_bf16 v[16:31], v[132:135], v[90:93], v[16:31]
	ds_read_b64_tr_b16 v[94:95], v213 offset:49152
	ds_read_b64_tr_b16 v[96:97], v213 offset:51200
	v_max3_f32 v81, v81, v114, v115
	v_max3_f32 v81, v81, v116, v117
	v_max3_f32 v81, v81, v118, v119
	v_max3_f32 v81, v81, v120, v121
	v_max3_f32 v81, v81, v122, v123
	v_max3_f32 v81, v81, v124, v125
	s_waitcnt lgkmcnt(2)
	v_mfma_f32_32x32x16_bf16 v[0:15], v[86:89], v[90:93], v[0:15]
	ds_read_b64_tr_b16 v[86:87], v214 offset:49152
	ds_read_b64_tr_b16 v[88:89], v214 offset:51200
	ds_read_b64_tr_b16 v[90:91], v213 offset:53248
	ds_read_b64_tr_b16 v[92:93], v213 offset:55296
	v_max3_f32 v81, v81, v126, v127
	v_max3_f32 v81, v81, v216, v217
	v_max3_f32 v81, v81, v218, v219
	v_max3_f32 v81, v81, v220, v221
	v_max3_f32 v81, v81, v222, v223
	v_max3_f32 v81, v81, v224, v225
	s_waitcnt lgkmcnt(4)
	v_mfma_f32_32x32x16_bf16 v[48:63], v[94:97], v[82:85], v[48:63]
	ds_read_b64_tr_b16 v[94:95], v215 offset:49152
	ds_read_b64_tr_b16 v[96:97], v215 offset:51200
	ds_read_b64_tr_b16 v[98:99], v214 offset:53248
	ds_read_b64_tr_b16 v[100:101], v214 offset:55296
	v_max3_f32 v81, v81, v226, v227
	v_max3_f32 v81, v81, v228, v229
	v_max3_f32 v107, v81, v230, v231
	v_add_f32_e32 v196, v194, v106
	v_add_f32_e32 v197, v195, v107
	v_mov_b64_e32 v[144:145], v[216:217]
	s_waitcnt lgkmcnt(6)
	v_mfma_f32_32x32x16_bf16 v[32:47], v[86:89], v[82:85], v[32:47]
	ds_read_b64_tr_b16 v[86:87], v248 offset:49152
	ds_read_b64_tr_b16 v[88:89], v248 offset:51200
	ds_read_b64_tr_b16 v[102:103], v215 offset:53248
	ds_read_b64_tr_b16 v[104:105], v215 offset:55296
	s_waitcnt lgkmcnt(6)
	v_mfma_f32_32x32x16_bf16 v[16:31], v[94:97], v[82:85], v[16:31]
	ds_read_b64_tr_b16 v[94:95], v248 offset:53248
	ds_read_b64_tr_b16 v[96:97], v248 offset:55296
	s_waitcnt vmcnt(0)
	s_waitcnt lgkmcnt(4)
	v_mfma_f32_32x32x16_bf16 v[0:15], v[86:89], v[82:85], v[0:15]
	v_cvt_pk_bf16_f32 v85, v110, v111
	v_cvt_pk_bf16_f32 v84, v108, v109
	v_cvt_pk_bf16_f32 v83, v138, v139
	v_cvt_pk_bf16_f32 v82, v136, v137
	s_nop 1
	v_mfma_f32_32x32x16_bf16 v[48:63], v[90:93], v[82:85], v[48:63]
	s_waitcnt lgkmcnt(0)
	s_barrier
	v_mfma_f32_32x32x16_bf16 v[32:47], v[98:101], v[82:85], v[32:47]
	v_mfma_f32_32x32x16_bf16 v[16:31], v[102:105], v[82:85], v[16:31]
	v_mfma_f32_32x32x16_bf16 v[0:15], v[94:97], v[82:85], v[0:15]
	s_cbranch_vccnz .LBB0_432

.LBB0_429:
	s_add_i32 s8, s76, 0
	v_add_u32_e32 v86, s8, v206
	ds_read_b128 v[82:85], v86
	ds_read_b128 v[86:89], v86 offset:4096
	v_add_u32_e32 v90, s8, v207
	v_add_u32_e32 v94, s8, v208
	v_add_u32_e32 v194, s8, v209
	s_waitcnt lgkmcnt(1)
	v_mfma_f32_32x32x16_bf16 v[128:143], v[82:85], v[160:163], v[64:79]
	ds_read_b128 v[82:85], v90
	ds_read_b128 v[90:93], v90 offset:4096
	v_exp_f32_e32 v95, v112
	v_exp_f32_e32 v245, v113
	v_exp_f32_e32 v145, v145
	v_exp_f32_e32 v244, v115
	v_exp_f32_e32 v115, v149
	v_cvt_pk_bf16_f32 v112, v95, v245
	s_waitcnt lgkmcnt(2)
	v_mfma_f32_32x32x16_bf16 v[96:111], v[86:89], v[160:163], v[64:79]
	ds_read_b128 v[86:89], v94
	ds_read_b128 v[232:235], v94 offset:4096
	ds_read_b128 v[236:239], v194
	ds_read_b128 v[240:243], v194 offset:4096
	v_exp_f32_e32 v94, v114
	v_exp_f32_e32 v114, v117
	v_exp_f32_e32 v156, v156
	s_add_i32 s8, s77, s76
	v_cvt_pk_bf16_f32 v113, v94, v244
	s_cmpk_eq_i32 s8, 0x2000
	s_waitcnt lgkmcnt(5)
	v_mfma_f32_32x32x16_bf16 v[128:143], v[82:85], v[164:167], v[128:143]
	v_exp_f32_e32 v85, v144
	v_exp_f32_e32 v84, v146
	v_exp_f32_e32 v144, v147
	s_cselect_b32 s9, s71, 0x2000
	v_cvt_pk_bf16_f32 v82, v85, v145
	s_cmpk_lg_i32 s8, 0x6000
	s_cselect_b32 s76, s9, 0
	s_waitcnt lgkmcnt(4)
	v_mfma_f32_32x32x16_bf16 v[96:111], v[90:93], v[164:167], v[96:111]
	v_add_f32_e32 v90, v94, v244
	v_add_f32_e32 v91, v95, v245
	v_add_f32_e32 v92, v84, v144
	v_add_f32_e32 v93, v85, v145
	v_exp_f32_e32 v94, v120
	v_add_f32_e32 v90, v90, v92
	v_add_f32_e32 v91, v91, v93
	v_exp_f32_e32 v92, v116
	v_exp_f32_e32 v93, v148
	s_waitcnt lgkmcnt(3)
	v_mfma_f32_32x32x16_bf16 v[128:143], v[86:89], v[168:171], v[128:143]
	v_add_f32_e32 v87, v90, v91
	v_cvt_pk_bf16_f32 v83, v84, v144
	v_add_f32_e32 v84, v92, v114
	v_add_f32_e32 v85, v93, v115
	v_exp_f32_e32 v86, v119
	v_add_f32_e32 v89, v84, v85
	v_exp_f32_e32 v85, v118
	v_exp_f32_e32 v88, v150
	v_exp_f32_e32 v90, v151
	s_waitcnt lgkmcnt(2)
	v_mfma_f32_32x32x16_bf16 v[96:111], v[232:235], v[168:171], v[96:111]
	v_cvt_pk_bf16_f32 v114, v92, v114
	v_cvt_pk_bf16_f32 v84, v93, v115
	v_add_f32_e32 v95, v85, v86
	v_add_f32_e32 v233, v88, v90
	v_cvt_pk_bf16_f32 v115, v85, v86
	v_cvt_pk_bf16_f32 v85, v88, v90
	ds_read_b64_tr_b16 v[90:91], v213 offset:24576
	ds_read_b64_tr_b16 v[92:93], v213 offset:26624
	v_exp_f32_e32 v232, v121
	v_exp_f32_e32 v88, v152
	v_exp_f32_e32 v86, v153
	ds_read_b64_tr_b16 v[116:117], v214 offset:24576
	ds_read_b64_tr_b16 v[118:119], v214 offset:26624
	ds_read_b64_tr_b16 v[144:145], v213 offset:28672
	ds_read_b64_tr_b16 v[146:147], v213 offset:30720
	v_add_f32_e32 v120, v94, v232
	v_add_f32_e32 v121, v95, v233
	s_waitcnt lgkmcnt(4)
	v_mfma_f32_32x32x16_bf16 v[48:63], v[90:93], v[112:115], v[48:63]
	v_add_f32_e32 v90, v88, v86
	v_add_f32_e32 v91, v89, v87
	v_exp_f32_e32 v234, v122
	v_add_f32_e32 v152, v120, v90
	v_add_f32_e32 v153, v121, v91
	ds_read_b64_tr_b16 v[90:91], v215 offset:24576
	ds_read_b64_tr_b16 v[92:93], v215 offset:26624
	ds_read_b64_tr_b16 v[148:149], v214 offset:28672
	ds_read_b64_tr_b16 v[150:151], v214 offset:30720
	v_exp_f32_e32 v235, v154
	v_exp_f32_e32 v87, v124
	v_exp_f32_e32 v89, v125
	v_mfma_f32_32x32x16_bf16 v[128:143], v[236:239], v[172:175], v[128:143]
	v_exp_f32_e32 v236, v123
	v_exp_f32_e32 v237, v155
	v_add_f32_e32 v239, v152, v153
	v_exp_f32_e32 v238, v159
	s_min_u32 s8, s4, 32
	s_min_u32 s10, s4, 33
	s_lshl_b32 s8, s8, 17
	s_waitcnt lgkmcnt(6)
	v_mfma_f32_32x32x16_bf16 v[32:47], v[116:119], v[112:115], v[32:47]
	ds_read_b64_tr_b16 v[116:117], v248 offset:24576
	ds_read_b64_tr_b16 v[118:119], v248 offset:26624
	ds_read_b64_tr_b16 v[120:121], v215 offset:28672
	ds_read_b64_tr_b16 v[122:123], v215 offset:30720
	ds_read_b64_tr_b16 v[152:153], v248 offset:28672
	ds_read_b64_tr_b16 v[154:155], v248 offset:30720
	s_add_u32 s8, s36, s8
	s_addc_u32 s9, s37, 0
	s_waitcnt lgkmcnt(8)
	v_mfma_f32_32x32x16_bf16 v[16:31], v[90:93], v[112:115], v[16:31]
	v_add_f32_e32 v92, v234, v236
	v_add_f32_e32 v93, v235, v237
	v_cvt_pk_bf16_f32 v90, v94, v232
	v_add_f32_e32 v95, v92, v93
	v_cvt_pk_bf16_f32 v91, v234, v236
	v_cvt_pk_bf16_f32 v92, v87, v89
	v_exp_f32_e32 v94, v158
	s_waitcnt lgkmcnt(4)
	v_mfma_f32_32x32x16_bf16 v[0:15], v[116:119], v[112:115], v[0:15]
	v_exp_f32_e32 v112, v126
	v_exp_f32_e32 v114, v127
	v_add_f32_e32 v113, v87, v89
	v_max_f32_e32 v89, v128, v128
	v_cvt_pk_bf16_f32 v93, v112, v114
	s_nop 1
	v_mfma_f32_32x32x16_bf16 v[48:63], v[144:147], v[90:93], v[48:63]
	v_exp_f32_e32 v144, v157
	v_cvt_pk_bf16_f32 v147, v94, v238
	v_cvt_pk_bf16_f32 v145, v235, v237
	v_add_f32_e32 v115, v156, v144
	v_add_f32_e32 v112, v112, v114
	v_add_f32_e32 v113, v113, v115
	v_add_f32_e32 v114, v94, v238
	v_add_f32_e32 v115, v95, v239
	v_mfma_f32_32x32x16_bf16 v[32:47], v[148:151], v[90:93], v[32:47]
	v_add_f32_e32 v112, v112, v114
	v_add_f32_e32 v113, v113, v115
	v_cvt_pk_bf16_f32 v146, v156, v144
	v_add_f32_e32 v87, v112, v113
	ds_read_b64_tr_b16 v[112:113], v213 offset:32768
	ds_read_b64_tr_b16 v[114:115], v213 offset:34816
	v_add_f32_e32 v194, v196, v87
	v_max_f32_e32 v87, v129, v129
	v_max_f32_e32 v87, v89, v87
	s_waitcnt lgkmcnt(4)
	v_mfma_f32_32x32x16_bf16 v[16:31], v[120:123], v[90:93], v[16:31]
	v_max3_f32 v87, v87, v130, v131
	v_max3_f32 v87, v87, v132, v133
	v_max3_f32 v87, v87, v134, v135
	v_max3_f32 v87, v87, v136, v137
	v_max3_f32 v87, v87, v138, v139
	v_max3_f32 v87, v87, v140, v141
	v_max3_f32 v87, v87, v142, v143
	s_waitcnt lgkmcnt(2)
	v_mfma_f32_32x32x16_bf16 v[0:15], v[152:155], v[90:93], v[0:15]
	ds_read_b64_tr_b16 v[90:91], v214 offset:32768
	ds_read_b64_tr_b16 v[92:93], v214 offset:34816
	ds_read_b64_tr_b16 v[116:117], v213 offset:36864
	ds_read_b64_tr_b16 v[118:119], v213 offset:38912
	v_cvt_pk_bf16_f32 v144, v88, v86
	s_waitcnt lgkmcnt(4)
	v_mfma_f32_32x32x16_bf16 v[48:63], v[112:115], v[82:85], v[48:63]
	ds_read_b64_tr_b16 v[112:113], v215 offset:32768
	ds_read_b64_tr_b16 v[114:115], v215 offset:34816
	ds_read_b64_tr_b16 v[120:121], v214 offset:36864
	ds_read_b64_tr_b16 v[122:123], v214 offset:38912
	s_waitcnt lgkmcnt(6)
	v_mfma_f32_32x32x16_bf16 v[32:47], v[90:93], v[82:85], v[32:47]
	ds_read_b64_tr_b16 v[90:91], v248 offset:32768
	ds_read_b64_tr_b16 v[92:93], v248 offset:34816
	ds_read_b64_tr_b16 v[124:125], v215 offset:36864
	ds_read_b64_tr_b16 v[126:127], v215 offset:38912
	v_mfma_f32_32x32x16_bf16 v[96:111], v[240:243], v[172:175], v[96:111]
	s_waitcnt lgkmcnt(6)
	v_mfma_f32_32x32x16_bf16 v[16:31], v[112:115], v[82:85], v[16:31]
	ds_read_b64_tr_b16 v[112:113], v248 offset:36864
	ds_read_b64_tr_b16 v[114:115], v248 offset:38912
	s_nop 7
	v_max3_f32 v87, v87, v96, v97
	v_max3_f32 v87, v87, v98, v99
	s_waitcnt vmcnt(0)
	s_waitcnt lgkmcnt(0)
	s_barrier
	v_mfma_f32_32x32x16_bf16 v[0:15], v[90:93], v[82:85], v[0:15]
	v_lshl_add_u64 v[82:83], v[180:181], 1, s[8:9]
	s_add_i32 s8, s43, s76
	v_lshl_add_u64 v[82:83], v[82:83], 0, s[24:25]
	s_mov_b32 s9, m0
	s_mov_b32 m0, s8
	s_nop 0
	global_load_lds_dwordx4 v[82:83], off
	s_mov_b32 m0, s9
	s_lshl_b32 s8, s10, 17
	v_max3_f32 v87, v87, v100, v101
	s_add_u32 s8, s26, s8
	v_mfma_f32_32x32x16_bf16 v[48:63], v[116:119], v[144:147], v[48:63]
	v_max3_f32 v87, v87, v102, v103
	s_addc_u32 s9, s27, 0
	v_max3_f32 v87, v87, v104, v105
	s_add_u32 s8, s8, 0x40000
	v_max3_f32 v87, v87, v106, v107
	s_addc_u32 s9, s9, 0
	v_max3_f32 v87, v87, v108, v109
	v_mfma_f32_32x32x16_bf16 v[32:47], v[120:123], v[144:147], v[32:47]
	v_lshl_add_u64 v[82:83], v[176:177], 1, s[8:9]
	s_mov_b32 s10, m0
	s_mov_b32 m0, s65
	s_nop 0
	global_load_lds_dwordx4 v[82:83], off
	s_mov_b32 m0, s10
	v_max3_f32 v87, v87, v110, v111
	v_lshl_add_u64 v[82:83], v[178:179], 1, s[8:9]
	s_mov_b32 s8, m0
	s_mov_b32 m0, s66
	s_nop 0
	global_load_lds_dwordx4 v[82:83], off
	s_mov_b32 m0, s8
	v_add_f32_e32 v87, v195, v87
	v_cmp_gt_f32_e32 vcc, v87, v81
	v_mfma_f32_32x32x16_bf16 v[16:31], v[124:127], v[144:147], v[16:31]
	v_mfma_f32_32x32x16_bf16 v[0:15], v[112:115], v[144:147], v[0:15]
	s_cbranch_vccz .LBB0_423
	ds_bpermute_b32 v82, v204, v87
	v_max_f32_e32 v83, v87, v87
	s_waitcnt lgkmcnt(0)
	v_max_f32_e32 v82, v82, v82
	v_max_f32_e32 v112, v83, v82
	v_cmp_gt_f32_e32 vcc, v112, v81
	s_and_saveexec_b64 s[8:9], vcc
	s_cbranch_execz .LBB0_422
	v_sub_f32_e32 v65, v112, v195
	v_exp_f32_e64 v64, -v65
	v_xor_b32_e32 v80, 0x80000000, v112
	v_mov_b32_e32 v81, v80
	v_sub_f32_e32 v128, v128, v65
	v_mul_f32_e32 v194, v194, v64
	v_pk_mul_f32 v[62:63], v[62:63], v[64:65] op_sel_hi:[1,0]
	v_pk_mul_f32 v[60:61], v[60:61], v[64:65] op_sel_hi:[1,0]
	v_pk_mul_f32 v[58:59], v[58:59], v[64:65] op_sel_hi:[1,0]
	v_pk_mul_f32 v[56:57], v[56:57], v[64:65] op_sel_hi:[1,0]
	v_pk_mul_f32 v[54:55], v[54:55], v[64:65] op_sel_hi:[1,0]
	v_pk_mul_f32 v[52:53], v[52:53], v[64:65] op_sel_hi:[1,0]
	v_pk_mul_f32 v[50:51], v[50:51], v[64:65] op_sel_hi:[1,0]
	v_pk_mul_f32 v[48:49], v[48:49], v[64:65] op_sel_hi:[1,0]
	v_pk_mul_f32 v[46:47], v[46:47], v[64:65] op_sel_hi:[1,0]
	v_pk_mul_f32 v[44:45], v[44:45], v[64:65] op_sel_hi:[1,0]
	v_pk_mul_f32 v[42:43], v[42:43], v[64:65] op_sel_hi:[1,0]
	v_pk_mul_f32 v[40:41], v[40:41], v[64:65] op_sel_hi:[1,0]
	v_pk_mul_f32 v[38:39], v[38:39], v[64:65] op_sel_hi:[1,0]
	v_pk_mul_f32 v[36:37], v[36:37], v[64:65] op_sel_hi:[1,0]
	v_pk_mul_f32 v[34:35], v[34:35], v[64:65] op_sel_hi:[1,0]
	v_pk_mul_f32 v[32:33], v[32:33], v[64:65] op_sel_hi:[1,0]
	v_pk_mul_f32 v[30:31], v[30:31], v[64:65] op_sel_hi:[1,0]
	v_pk_mul_f32 v[28:29], v[28:29], v[64:65] op_sel_hi:[1,0]
	v_pk_mul_f32 v[26:27], v[26:27], v[64:65] op_sel_hi:[1,0]
	v_pk_mul_f32 v[24:25], v[24:25], v[64:65] op_sel_hi:[1,0]
	v_pk_mul_f32 v[22:23], v[22:23], v[64:65] op_sel_hi:[1,0]
	v_pk_mul_f32 v[20:21], v[20:21], v[64:65] op_sel_hi:[1,0]
	v_pk_mul_f32 v[18:19], v[18:19], v[64:65] op_sel_hi:[1,0]
	v_pk_mul_f32 v[16:17], v[16:17], v[64:65] op_sel_hi:[1,0]
	v_pk_mul_f32 v[14:15], v[14:15], v[64:65] op_sel_hi:[1,0]
	v_pk_mul_f32 v[12:13], v[12:13], v[64:65] op_sel_hi:[1,0]
	v_pk_mul_f32 v[10:11], v[10:11], v[64:65] op_sel_hi:[1,0]
	v_pk_mul_f32 v[8:9], v[8:9], v[64:65] op_sel_hi:[1,0]
	v_pk_mul_f32 v[6:7], v[6:7], v[64:65] op_sel_hi:[1,0]
	v_pk_mul_f32 v[4:5], v[4:5], v[64:65] op_sel_hi:[1,0]
	v_pk_mul_f32 v[2:3], v[2:3], v[64:65] op_sel_hi:[1,0]
	v_pk_mul_f32 v[0:1], v[0:1], v[64:65] op_sel_hi:[1,0]
	v_sub_f32_e32 v129, v129, v65
	v_sub_f32_e32 v130, v130, v65
	v_sub_f32_e32 v131, v131, v65
	v_sub_f32_e32 v132, v132, v65
	v_sub_f32_e32 v133, v133, v65
	v_sub_f32_e32 v134, v134, v65
	v_sub_f32_e32 v135, v135, v65
	v_sub_f32_e32 v136, v136, v65
	v_sub_f32_e32 v137, v137, v65
	v_sub_f32_e32 v138, v138, v65
	v_sub_f32_e32 v139, v139, v65
	v_sub_f32_e32 v140, v140, v65
	v_sub_f32_e32 v141, v141, v65
	v_sub_f32_e32 v142, v142, v65
	v_sub_f32_e32 v143, v143, v65
	v_sub_f32_e32 v96, v96, v65
	v_sub_f32_e32 v97, v97, v65
	v_sub_f32_e32 v98, v98, v65
	v_sub_f32_e32 v99, v99, v65
	v_sub_f32_e32 v100, v100, v65
	v_sub_f32_e32 v101, v101, v65
	v_sub_f32_e32 v102, v102, v65
	v_sub_f32_e32 v103, v103, v65
	v_sub_f32_e32 v104, v104, v65
	v_sub_f32_e32 v105, v105, v65
	v_sub_f32_e32 v106, v106, v65
	v_sub_f32_e32 v107, v107, v65
	v_sub_f32_e32 v108, v108, v65
	v_sub_f32_e32 v109, v109, v65
	v_sub_f32_e32 v110, v110, v65
	v_sub_f32_e32 v111, v111, v65
	v_mov_b32_e32 v82, v80
	v_mov_b32_e32 v83, v80
	v_mov_b32_e32 v84, v80
	v_mov_b32_e32 v85, v80
	v_mov_b32_e32 v86, v80
	v_mov_b32_e32 v87, v80
	v_mov_b32_e32 v88, v80
	v_mov_b32_e32 v89, v80
	v_mov_b32_e32 v90, v80
	v_mov_b32_e32 v91, v80
	v_mov_b32_e32 v92, v80
	v_mov_b32_e32 v93, v80
	v_mov_b32_e32 v94, v80
	v_mov_b32_e32 v95, v80
	v_mov_b64_e32 v[64:65], v[80:81]
	v_mov_b32_e32 v195, v112
	v_mov_b64_e32 v[66:67], v[82:83]
	v_mov_b64_e32 v[68:69], v[84:85]
	v_mov_b64_e32 v[70:71], v[86:87]
	v_mov_b64_e32 v[72:73], v[88:89]
	v_mov_b64_e32 v[74:75], v[90:91]
	v_mov_b64_e32 v[76:77], v[92:93]
	v_mov_b64_e32 v[78:79], v[94:95]
	s_branch .LBB0_422
